# attention: next item K/V/Q rows touched into L2 during the current item's compute; relaxed first-tile waits in final GEMM
# speedup vs baseline: 1.0070x; 1.0070x over previous
; #define LAS __attribute__((address_space(3)))
; __device__ __forceinline__ void attn_item(const Args& a, LAS unsigned char* lds, int item, int tid, int wave, int lane) {
;     ...
;         const int kc = (t >> 2) < 192 ? (t >> 2) : 191, kpos = q0 - 128 + kc, kposc = kpos < 0 ? 0 : kpos;
;         const bf16_t* kp = P + (rowbase + kposc) * NIN + PC_KA + kvh * 64 + grp * 16; kk[it][0] = *(const u32x4*)kp; kk[it][1] = *(const u32x4*)(kp + 8);
;         const bf16_t* vp = P + (rowbase + kposc) * NIN + PC_VA + kvh * 64 + grp * 16; vv[it][0] = *(const u32x4*)vp; vv[it][1] = *(const u32x4*)(vp + 8);
;         const float* tkp = rope + (rowbase + kposc) * 16;
; #pragma unroll
;         for (int q = 0; q < 4; ++q) tk[it][q] = *(const f32x4*)(tkp + 4 * q);
;         const int qi = (t >> 2) & 63, gq = t >> 8;
;         const size_t row = rowbase + q0 + qi;
;     ...
;             for (int q = 0; q < 4; ++q) { o0[q] = cvt_pk_bf16(x[2 * q] * 0.125f, x[2 * q + 1] * 0.125f); o1[q] = cvt_pk_bf16(x[8 + 2 * q] * 0.125f, x[8 + 2 * q + 1] * 0.125f); }
;             *(LAS u32x4*)(QS + (gq * 64 + qi) * LP + grp * 16) = o0; *(LAS u32x4*)(QS + (gq * 64 + qi) * LP + grp * 16 + 8) = o1;
;         }
;     }
;     __syncthreads();
;     const int g = wave >> 1;
;     const float sink = a.sinks[kvh * 4 + g];
;     constexpr float LOG2E = 1.4426950408889634f;
; #pragma unroll 1
;     for (int rr = 0; rr < 2; ++rr) {
;         const int rt = 2 * (wave & 1) + rr;
;         const bf16x8 bq0 = *(const LAS bf16x8*)(QS + (g * 64 + 16 * rt + fr) * LP + 8 * fq), bq1 = *(const LAS bf16x8*)(QS + (g * 64 + 16 * rt + fr) * LP + 32 + 8 * fq);
;         f32x4 s[9];
; #pragma unroll
;         for (int t = 0; t < 9; ++t) {
;             const LAS bf16_t* kp = KS + (16 * (rt + t) + fr) * LP + 8 * fq;
;             const bf16x8 k0 = *(const LAS bf16x8*)kp, k1 = *(const LAS bf16x8*)(kp + 32);
;             f32x4 v = (f32x4){0.f, 0.f, 0.f, 0.f};
;             v = MFMA16(k0, bq0, v); v = MFMA16(k1, bq1, v); s[t] = v;
;         }
; #pragma unroll
;         for (int i = 0; i < 4; ++i) { if (!(4 * fq + i > fr)) s[0][i] = -INFINITY; if (!(4 * fq + i <= fr)) s[8][i] = -INFINITY; }
;         if (q0 < 128) {
; #pragma unroll
;             for (int t = 0; t < 9; ++t)
; #pragma unroll
;                 for (int i = 0; i < 4; ++i) { if (q0 - 128 + 16 * (rt + t) + 4 * fq + i < 0) s[t][i] = -INFINITY; }
.LBB0_1100:
	s_or_b64 exec, exec, s[34:35]
	v_mul_f32_e32 v4, 0x3e000000, v37
	v_mul_f32_e32 v0, 0x3e000000, v0
	v_mul_f32_e32 v3, 0x3e000000, v36
	v_cvt_pk_bf16_f32 v4, v3, v4
	v_mul_f32_e32 v1, 0x3e000000, v1
	v_cvt_pk_bf16_f32 v8, v0, v1
	v_mul_f32_e32 v0, 0x3e000000, v34
	v_mul_f32_e32 v1, 0x3e000000, v35
	v_cvt_pk_bf16_f32 v5, v0, v1
	v_mul_f32_e32 v0, 0x3e000000, v24
	v_mul_f32_e32 v1, 0x3e000000, v25
	v_cvt_pk_bf16_f32 v9, v0, v1
	v_mul_f32_e32 v0, 0x3e000000, v32
	v_mul_f32_e32 v1, 0x3e000000, v33
	v_cvt_pk_bf16_f32 v6, v0, v1
	v_mul_f32_e32 v0, 0x3e000000, v28
	s_lshl_b32 s22, s44, 2
	v_mul_f32_e32 v1, 0x3e000000, v29
	v_cvt_pk_bf16_f32 v10, v0, v1
	v_mul_f32_e32 v0, 0x3e000000, v30
	s_add_i32 s22, s22, s33
	v_mul_f32_e32 v1, 0x3e000000, v31
	v_cvt_pk_bf16_f32 v7, v0, v1
	v_mul_f32_e32 v0, 0x3e000000, v20
	s_lshl_b32 s34, s22, 2
	v_mul_f32_e32 v1, 0x3e000000, v21
	v_cvt_pk_bf16_f32 v11, v0, v1
	v_mov_b32_e32 v0, s34
	ds_write_b128 v106, v[4:7] offset:53248
	ds_write_b128 v106, v[8:11] offset:53264
	s_waitcnt lgkmcnt(0)
	s_barrier
	global_load_dword v40, v0, s[62:63]
	v_and_b32_e32 v1, 64, v107
	v_xor_b32_e32 v0, 16, v107
	v_add_u32_e32 v1, 64, v1
	v_cmp_lt_i32_e32 vcc, v0, v1
	s_cmpk_lt_u32 s36, 0x80
	s_cselect_b64 s[34:35], -1, 0
	v_cndmask_b32_e32 v0, v107, v0, vcc
	v_lshlrev_b32_e32 v41, 2, v0
	v_xor_b32_e32 v0, 32, v107
	v_cmp_lt_i32_e32 vcc, v0, v1
	s_or_b32 s37, s37, 0xffffff80
	s_lshl_b32 s22, s22, 6
	v_cndmask_b32_e32 v0, v107, v0, vcc
	s_mov_b32 s45, 0
	v_lshlrev_b32_e32 v42, 2, v0
	s_sub_i32 s44, 0, s37
	v_or_b32_e32 v43, s36, v92
	s_mov_b64 s[36:37], -1
	s_lshl_b32 s22, s22, 1
	s_waitcnt vmcnt(0)
	s_cmp_eq_u32 s43, 3
	s_cbranch_scc1 .Lapf_skip
	s_add_i32 s32, s43, 1
	s_lshl_b32 s32, s32, 5
	s_add_i32 s32, s32, s81
	s_bfe_u32 s53, s32, 0x10005
	s_lshr_b32 s54, s32, 6
	s_lshl_b32 s55, s92, 1
	s_add_i32 s54, s54, s55
	s_lshl_b32 s54, s54, 11
	s_lshl_b32 s55, s81, 6
	s_add_i32 s70, s54, s55
	s_add_i32 s71, s55, 0xffffff80
	s_lshl_b32 s79, s53, 7
	s_add_i32 s79, s79, 0x1000
	s_lshl_b32 s80, s53, 9
	s_add_i32 s80, s80, 0xc00
	s_movk_i32 s82, 0x2400
	s_movk_i32 s83, 0xc0
	v_add_u32_e32 v148, s71, v153
	v_max_i32_e32 v148, 0, v148
	v_add_u32_e32 v148, s54, v148
	v_mul_lo_u32 v148, v148, s82
	v_add_u32_e32 v148, s79, v148
	v_subrev_u32_e32 v149, s83, v153
	v_min_u32_e32 v149, 0xff, v149
	v_lshrrev_b32_e32 v150, 2, v149
	v_and_b32_e32 v149, 3, v149
	v_add_u32_e32 v150, s70, v150
	v_mul_lo_u32 v150, v150, s82
	v_lshl_add_u32 v150, v149, 7, v150
	v_add_u32_e32 v150, s80, v150
	v_cmp_gt_u32_e64 s[66:67], s83, v153
	s_nop 1
	v_cndmask_b32_e64 v148, v150, v148, s[66:67]
	global_load_dword v151, v148, s[68:69]
	global_load_dword v151, v148, s[68:69] offset:256
.Lapf_skip:
	s_branch .LBB0_1103
.LBB0_1101:
	s_cmp_lt_u32 s52, s44
	s_cselect_b64 vcc, -1, 0
	s_cmp_lt_u32 s51, s44
	v_cndmask_b32_e32 v31, v31, v108, vcc
	v_cndmask_b32_e32 v30, v30, v108, vcc
	v_cndmask_b32_e32 v29, v29, v108, vcc
	v_cndmask_b32_e32 v28, v28, v108, vcc
	s_cselect_b64 vcc, -1, 0
	s_cmp_lt_u32 s50, s44
	v_cndmask_b32_e32 v27, v27, v108, vcc
	v_cndmask_b32_e32 v26, v26, v108, vcc
	v_cndmask_b32_e32 v25, v25, v108, vcc
	v_cndmask_b32_e32 v24, v24, v108, vcc
	s_cselect_b64 vcc, -1, 0
	s_cmp_lt_u32 s49, s44
	v_cndmask_b32_e32 v23, v23, v108, vcc
	v_cndmask_b32_e32 v22, v22, v108, vcc
	v_cndmask_b32_e32 v21, v21, v108, vcc
	v_cndmask_b32_e32 v20, v20, v108, vcc
	s_cselect_b64 vcc, -1, 0
	s_cmp_lt_u32 s48, s44
	v_cndmask_b32_e32 v19, v19, v108, vcc
	v_cndmask_b32_e32 v18, v18, v108, vcc
	v_cndmask_b32_e32 v17, v17, v108, vcc
	v_cndmask_b32_e32 v16, v16, v108, vcc
	s_cselect_b64 vcc, -1, 0
	s_cmp_lt_u32 s47, s44
	v_cndmask_b32_e32 v15, v15, v108, vcc
	v_cndmask_b32_e32 v14, v14, v108, vcc
	v_cndmask_b32_e32 v13, v13, v108, vcc
	v_cndmask_b32_e32 v12, v12, v108, vcc
	s_cselect_b64 vcc, -1, 0
	s_cmp_lt_u32 s46, s44
	v_cndmask_b32_e32 v11, v11, v108, vcc
	v_cndmask_b32_e32 v10, v10, v108, vcc
	v_cndmask_b32_e32 v9, v9, v108, vcc
	v_cndmask_b32_e32 v8, v8, v108, vcc
	s_cselect_b64 vcc, -1, 0
	v_cndmask_b32_e32 v7, v7, v108, vcc
	v_cndmask_b32_e32 v6, v6, v108, vcc
	v_cndmask_b32_e32 v5, v5, v108, vcc
	v_cndmask_b32_e32 v4, v4, v108, vcc
	v_mov_b32_e32 v0, 0xff800000
	v_mov_b32_e32 v36, 0xff800000
	v_mov_b32_e32 v3, 0xff800000
	v_mov_b32_e32 v1, 0xff800000

.LBB0_1721:
	s_add_u32 s6, s24, 0xb0080
	s_addc_u32 s7, s25, 0
	s_add_u32 s48, s22, 0x100
	v_mov_b32_e32 v0, 0
	s_addc_u32 s49, s23, 0
	s_mov_b32 s50, -2
	s_add_u32 s22, s6, 0xfff50080
	s_addc_u32 s23, s7, -1
	s_cmp_eq_u32 s50, 40
	s_cselect_b32 s25, s19, s23
	s_cselect_b32 s24, s18, s22
	s_cselect_b32 s23, s21, s49
	s_cselect_b32 s22, s20, s48
	v_lshl_add_u64 v[216:217], s[6:7], 0, v[152:153]
	s_add_i32 m0, s29, 0xc000
	s_nop 0
	global_load_lds_dwordx4 v[216:217], off
	v_lshl_add_u64 v[216:217], s[6:7], 0, v[162:163]
	s_add_i32 m0, s29, 0xe000
	s_nop 0
	global_load_lds_dwordx4 v[216:217], off
	s_cmp_eq_u32 s101, 1
	s_cbranch_scc1 .Lpk1722_r1
	s_waitcnt vmcnt(8)
	s_branch .Lpk1722_j1
.Lpk1722_r1:
	s_waitcnt vmcnt(40)
.Lpk1722_j1:
	s_waitcnt lgkmcnt(0)
	s_barrier
	s_setprio 1
	s_waitcnt lgkmcnt(0)
	v_mfma_f32_16x16x32_bf16 v[124:127], v[128:131], v[176:179], 0
	v_mfma_f32_16x16x32_bf16 v[120:123], v[136:139], v[176:179], 0
	v_mfma_f32_16x16x32_bf16 v[108:111], v[128:131], v[184:187], 0
	v_mfma_f32_16x16x32_bf16 v[104:107], v[136:139], v[184:187], 0
	v_mfma_f32_16x16x32_bf16 v[92:95], v[128:131], v[192:195], 0
	v_mfma_f32_16x16x32_bf16 v[88:91], v[136:139], v[192:195], 0
	v_mfma_f32_16x16x32_bf16 v[76:79], v[128:131], v[208:211], 0
	v_mfma_f32_16x16x32_bf16 v[72:75], v[136:139], v[208:211], 0
	v_mfma_f32_16x16x32_bf16 v[124:127], v[132:135], v[180:183], v[124:127]
	v_mfma_f32_16x16x32_bf16 v[120:123], v[140:143], v[180:183], v[120:123]
	v_mfma_f32_16x16x32_bf16 v[108:111], v[132:135], v[188:191], v[108:111]
	v_mfma_f32_16x16x32_bf16 v[104:107], v[140:143], v[188:191], v[104:107]
	v_mfma_f32_16x16x32_bf16 v[92:95], v[132:135], v[204:207], v[92:95]
	v_mfma_f32_16x16x32_bf16 v[88:91], v[140:143], v[204:207], v[88:91]
	v_mfma_f32_16x16x32_bf16 v[76:79], v[132:135], v[212:215], v[76:79]
	v_mfma_f32_16x16x32_bf16 v[72:75], v[140:143], v[212:215], v[72:75]
	s_setprio 0
	s_setprio 1
	v_mfma_f32_16x16x32_bf16 v[116:119], v[144:147], v[176:179], 0
	v_mfma_f32_16x16x32_bf16 v[112:115], v[168:171], v[176:179], 0
	v_mfma_f32_16x16x32_bf16 v[100:103], v[144:147], v[184:187], 0
	v_mfma_f32_16x16x32_bf16 v[96:99], v[168:171], v[184:187], 0
	v_mfma_f32_16x16x32_bf16 v[84:87], v[144:147], v[192:195], 0
	v_mfma_f32_16x16x32_bf16 v[80:83], v[168:171], v[192:195], 0
	v_mfma_f32_16x16x32_bf16 v[68:71], v[144:147], v[208:211], 0
	v_mfma_f32_16x16x32_bf16 v[64:67], v[168:171], v[208:211], 0
	v_mfma_f32_16x16x32_bf16 v[116:119], v[148:151], v[180:183], v[116:119]
	v_mfma_f32_16x16x32_bf16 v[112:115], v[172:175], v[180:183], v[112:115]
	v_mfma_f32_16x16x32_bf16 v[100:103], v[148:151], v[188:191], v[100:103]
	v_mfma_f32_16x16x32_bf16 v[96:99], v[172:175], v[188:191], v[96:99]
	v_mfma_f32_16x16x32_bf16 v[84:87], v[148:151], v[204:207], v[84:87]
	v_mfma_f32_16x16x32_bf16 v[80:83], v[172:175], v[204:207], v[80:83]
	v_mfma_f32_16x16x32_bf16 v[68:71], v[148:151], v[212:215], v[68:71]
	v_mfma_f32_16x16x32_bf16 v[64:67], v[172:175], v[212:215], v[64:67]
	s_setprio 0
	s_barrier
	s_add_i32 s51, s41, s28
	v_lshl_add_u64 v[216:217], s[22:23], 0, v[156:157]
	s_mov_b32 m0, s51
	ds_read_b128 v[176:179], v201 offset:16384
	ds_read_b128 v[180:183], v201 offset:17408
	global_load_lds_dwordx4 v[216:217], off
	s_add_i32 m0, s51, 0x2000
	s_add_u32 s52, s22, 0xb0000
	v_lshl_add_u64 v[218:219], s[22:23], 0, v[160:161]
	s_addc_u32 s53, s23, 0
	s_add_i32 s51, s42, s28
	ds_read_b128 v[184:187], v201 offset:18432
	ds_read_b128 v[188:191], v201 offset:19456
	global_load_lds_dwordx4 v[218:219], off
	v_lshl_add_u64 v[220:221], s[52:53], 0, v[156:157]
	s_mov_b32 m0, s51
	v_lshl_add_u64 v[222:223], s[24:25], 0, v[158:159]
	ds_read_b128 v[192:195], v201 offset:20480
	global_load_lds_dwordx4 v[220:221], off
	v_lshl_add_u64 v[220:221], s[52:53], 0, v[160:161]
	s_add_i32 m0, s51, 0x2000
	ds_read_b128 v[204:207], v201 offset:21504
	global_load_lds_dwordx4 v[220:221], off
	v_lshl_add_u64 v[220:221], s[24:25], 0, v[154:155]
	s_mov_b32 m0, s29
	ds_read_b128 v[208:211], v201 offset:22528
	global_load_lds_dwordx4 v[220:221], off
	s_mov_b32 m0, s30
	ds_read_b128 v[212:215], v201 offset:23552
	global_load_lds_dwordx4 v[222:223], off
	s_cmp_eq_u32 s101, 1
	s_cbranch_scc1 .Lpk1722_r2
	s_waitcnt vmcnt(8)
	s_branch .Lpk1722_j2

.Lpk1722_j2:
	s_mov_b32 s101, 0
	s_waitcnt lgkmcnt(0)
	s_barrier
	s_setprio 1
	s_waitcnt lgkmcnt(0)
	v_mfma_f32_16x16x32_bf16 v[60:63], v[128:131], v[176:179], 0
	v_mfma_f32_16x16x32_bf16 v[56:59], v[136:139], v[176:179], 0
	v_mfma_f32_16x16x32_bf16 v[44:47], v[128:131], v[184:187], 0
	v_mfma_f32_16x16x32_bf16 v[40:43], v[136:139], v[184:187], 0
	v_mfma_f32_16x16x32_bf16 v[28:31], v[128:131], v[192:195], 0
	v_mfma_f32_16x16x32_bf16 v[24:27], v[136:139], v[192:195], 0
	v_mfma_f32_16x16x32_bf16 v[12:15], v[128:131], v[208:211], 0
	v_mfma_f32_16x16x32_bf16 v[8:11], v[136:139], v[208:211], 0
	v_mfma_f32_16x16x32_bf16 v[60:63], v[132:135], v[180:183], v[60:63]
	v_mfma_f32_16x16x32_bf16 v[56:59], v[140:143], v[180:183], v[56:59]
	v_mfma_f32_16x16x32_bf16 v[44:47], v[132:135], v[188:191], v[44:47]
	v_mfma_f32_16x16x32_bf16 v[40:43], v[140:143], v[188:191], v[40:43]
	v_mfma_f32_16x16x32_bf16 v[28:31], v[132:135], v[204:207], v[28:31]
	v_mfma_f32_16x16x32_bf16 v[24:27], v[140:143], v[204:207], v[24:27]
	v_mfma_f32_16x16x32_bf16 v[12:15], v[132:135], v[212:215], v[12:15]
	v_mfma_f32_16x16x32_bf16 v[8:11], v[140:143], v[212:215], v[8:11]
	s_setprio 0
	s_setprio 1
	v_mfma_f32_16x16x32_bf16 v[52:55], v[144:147], v[176:179], 0
	v_mfma_f32_16x16x32_bf16 v[48:51], v[168:171], v[176:179], 0
	v_mfma_f32_16x16x32_bf16 v[36:39], v[144:147], v[184:187], 0
	v_mfma_f32_16x16x32_bf16 v[32:35], v[168:171], v[184:187], 0
	v_mfma_f32_16x16x32_bf16 v[20:23], v[144:147], v[192:195], 0
	v_mfma_f32_16x16x32_bf16 v[16:19], v[168:171], v[192:195], 0
	v_mfma_f32_16x16x32_bf16 v[4:7], v[144:147], v[208:211], 0
	v_mfma_f32_16x16x32_bf16 v[0:3], v[168:171], v[208:211], 0
	v_mfma_f32_16x16x32_bf16 v[52:55], v[148:151], v[180:183], v[52:55]
	v_mfma_f32_16x16x32_bf16 v[48:51], v[172:175], v[180:183], v[48:51]
	v_mfma_f32_16x16x32_bf16 v[36:39], v[148:151], v[188:191], v[36:39]
	v_mfma_f32_16x16x32_bf16 v[32:35], v[172:175], v[188:191], v[32:35]
	v_mfma_f32_16x16x32_bf16 v[20:23], v[148:151], v[204:207], v[20:23]
	v_mfma_f32_16x16x32_bf16 v[16:19], v[172:175], v[204:207], v[16:19]
	v_mfma_f32_16x16x32_bf16 v[4:7], v[148:151], v[212:215], v[4:7]
	v_mfma_f32_16x16x32_bf16 v[0:3], v[172:175], v[212:215], v[0:3]
	s_setprio 0
	s_barrier
	s_branch .Lpk1722_seg3

;     __device__ __forceinline__ void operator()(Acc& acc, const Unit& u, int wr, int wc, int fr, int fq) const {
;     ...
;         const f32x4 g00 = *(const f32x4*)(gain + col0), g01 = *(const f32x4*)(gain + col0 + 4), g10 = *(const f32x4*)(gain + col0 + HALF), g11 = *(const f32x4*)(gain + col0 + HALF + 4);
; #pragma unroll
;         for (int ai = 0; ai < 2; ++ai)
; #pragma unroll
;             for (int m = 0; m < 4; ++m) {
;                 const int row = row0 + ai * HALF + m * 16;
;                 const float r = rsqrtf(__hip_atomic_load(ss + row, __ATOMIC_RELAXED, __HIP_MEMORY_SCOPE_AGENT) * (1.0f / DM) + NORM_EPS);
;                 float* op = out + (size_t)row * DM + col0;
;                 *(f32x4*)op = acc[ai][0][m][0] * r * g00; *(f32x4*)(op + 4) = acc[ai][0][m][1] * r * g01;
;                 *(f32x4*)(op + HALF) = acc[ai][1][m][0] * r * g10; *(f32x4*)(op + HALF + 4) = acc[ai][1][m][1] * r * g11;
.LBB0_1752:
	v_lshlrev_b64 v[80:81], 2, v[176:177]
	v_lshl_add_u64 v[8:9], s[86:87], 0, v[80:81]
	global_load_dwordx4 v[4:7], v[8:9], off offset:16
	global_load_dwordx4 v[12:15], v[8:9], off
	s_waitcnt lgkmcnt(0)
	global_load_dwordx4 v[0:3], v[8:9], off offset:528
	s_nop 0
	global_load_dwordx4 v[8:11], v[8:9], off offset:512
	global_load_dword v204, v[112:113], off sc1
	global_load_dword v205, v[188:189], off sc1
	global_load_dword v206, v[190:191], off sc1
	global_load_dword v207, v[192:193], off sc1
	global_load_dword v208, v[112:113], off offset:512 sc1
	global_load_dword v209, v[112:113], off offset:576 sc1
	global_load_dword v210, v[112:113], off offset:640 sc1
	global_load_dword v211, v[112:113], off offset:704 sc1
	s_nop 0
	s_waitcnt vmcnt(0)
	v_fmamk_f32 v82, v204, 0x3a800000, v203
	v_mul_f32_e32 v83, 0x4b800000, v82
	v_cmp_gt_f32_e32 vcc, s43, v82
	s_nop 1
	v_cndmask_b32_e32 v82, v82, v83, vcc
	v_rsq_f32_e32 v84, v82
	v_lshlrev_b64 v[82:83], 12, v[174:175]
	v_lshl_add_u64 v[82:83], s[72:73], 0, v[82:83]
	v_lshl_add_u64 v[86:87], v[82:83], 0, v[80:81]
	v_mul_f32_e32 v82, 0x45800000, v84
	v_cndmask_b32_e32 v82, v84, v82, vcc
	v_pk_mul_f32 v[174:175], v[178:179], v[82:83] op_sel_hi:[1,0]
	v_pk_mul_f32 v[84:85], v[126:127], v[82:83] op_sel_hi:[1,0]
	v_pk_mul_f32 v[124:125], v[124:125], v[82:83] op_sel_hi:[1,0]
	v_pk_mul_f32 v[122:123], v[122:123], v[82:83] op_sel_hi:[1,0]
	v_pk_mul_f32 v[126:127], v[120:121], v[82:83] op_sel_hi:[1,0]
	v_pk_mul_f32 v[118:119], v[118:119], v[82:83] op_sel_hi:[1,0]
	v_pk_mul_f32 v[176:177], v[116:117], v[82:83] op_sel_hi:[1,0]
	v_pk_mul_f32 v[178:179], v[114:115], v[82:83] op_sel_hi:[1,0]
	v_pk_mul_f32 v[84:85], v[14:15], v[84:85]
	v_pk_mul_f32 v[82:83], v[12:13], v[174:175]
	v_pk_mul_f32 v[116:117], v[6:7], v[122:123]
	v_pk_mul_f32 v[114:115], v[4:5], v[124:125]
	v_pk_mul_f32 v[120:121], v[10:11], v[118:119]
	v_pk_mul_f32 v[118:119], v[8:9], v[126:127]
	v_pk_mul_f32 v[124:125], v[2:3], v[178:179]
	v_pk_mul_f32 v[122:123], v[0:1], v[176:177]
	global_store_dwordx4 v[86:87], v[82:85], off
	global_store_dwordx4 v[86:87], v[114:117], off offset:16
	global_store_dwordx4 v[86:87], v[118:121], off offset:512
	global_store_dwordx4 v[86:87], v[122:125], off offset:528
	s_nop 1
	v_fmamk_f32 v82, v205, 0x3a800000, v203
	v_mul_f32_e32 v83, 0x4b800000, v82
	v_cmp_gt_f32_e32 vcc, s43, v82
	s_nop 1
	v_cndmask_b32_e32 v82, v82, v83, vcc
	v_rsq_f32_e32 v84, v82
	v_lshlrev_b64 v[82:83], 12, v[172:173]
	v_lshl_add_u64 v[82:83], s[72:73], 0, v[82:83]
	v_lshl_add_u64 v[86:87], v[82:83], 0, v[80:81]
	v_mul_f32_e32 v82, 0x45800000, v84
	v_cndmask_b32_e32 v82, v84, v82, vcc
	v_pk_mul_f32 v[108:109], v[108:109], v[82:83] op_sel_hi:[1,0]
	v_pk_mul_f32 v[84:85], v[110:111], v[82:83] op_sel_hi:[1,0]
	v_pk_mul_f32 v[104:105], v[104:105], v[82:83] op_sel_hi:[1,0]
	v_pk_mul_f32 v[106:107], v[106:107], v[82:83] op_sel_hi:[1,0]
	v_pk_mul_f32 v[100:101], v[100:101], v[82:83] op_sel_hi:[1,0]
	v_pk_mul_f32 v[102:103], v[102:103], v[82:83] op_sel_hi:[1,0]
	v_pk_mul_f32 v[110:111], v[96:97], v[82:83] op_sel_hi:[1,0]
	v_pk_mul_f32 v[114:115], v[98:99], v[82:83] op_sel_hi:[1,0]
	v_pk_mul_f32 v[84:85], v[14:15], v[84:85]
	v_pk_mul_f32 v[82:83], v[12:13], v[108:109]
	v_pk_mul_f32 v[98:99], v[6:7], v[106:107]
	v_pk_mul_f32 v[96:97], v[4:5], v[104:105]
	v_pk_mul_f32 v[102:103], v[10:11], v[102:103]
	v_pk_mul_f32 v[100:101], v[8:9], v[100:101]
	v_pk_mul_f32 v[106:107], v[2:3], v[114:115]
	v_pk_mul_f32 v[104:105], v[0:1], v[110:111]
	global_store_dwordx4 v[86:87], v[82:85], off
	global_store_dwordx4 v[86:87], v[96:99], off offset:16
	global_store_dwordx4 v[86:87], v[100:103], off offset:512
	global_store_dwordx4 v[86:87], v[104:107], off offset:528
	s_nop 1
	v_fmamk_f32 v82, v206, 0x3a800000, v203
	v_mul_f32_e32 v83, 0x4b800000, v82
	v_cmp_gt_f32_e32 vcc, s43, v82
	s_nop 1
	v_cndmask_b32_e32 v82, v82, v83, vcc
	v_rsq_f32_e32 v84, v82
	v_lshlrev_b64 v[82:83], 12, v[170:171]
	v_lshl_add_u64 v[82:83], s[72:73], 0, v[82:83]
	v_lshl_add_u64 v[86:87], v[82:83], 0, v[80:81]
	v_mul_f32_e32 v82, 0x45800000, v84
	v_cndmask_b32_e32 v82, v84, v82, vcc
	v_pk_mul_f32 v[96:97], v[144:145], v[82:83] op_sel_hi:[1,0]
	v_pk_mul_f32 v[84:85], v[94:95], v[82:83] op_sel_hi:[1,0]
	v_pk_mul_f32 v[94:95], v[142:143], v[82:83] op_sel_hi:[1,0]
	v_pk_mul_f32 v[98:99], v[140:141], v[82:83] op_sel_hi:[1,0]
	v_pk_mul_f32 v[102:103], v[146:147], v[82:83] op_sel_hi:[1,0]
	v_pk_mul_f32 v[100:101], v[136:137], v[82:83] op_sel_hi:[1,0]
	v_pk_mul_f32 v[106:107], v[148:149], v[82:83] op_sel_hi:[1,0]
	v_pk_mul_f32 v[104:105], v[138:139], v[82:83] op_sel_hi:[1,0]
	v_pk_mul_f32 v[84:85], v[14:15], v[84:85]
	v_pk_mul_f32 v[82:83], v[12:13], v[96:97]
	v_pk_mul_f32 v[96:97], v[6:7], v[98:99]
	v_pk_mul_f32 v[94:95], v[4:5], v[94:95]
	v_pk_mul_f32 v[100:101], v[10:11], v[100:101]
	v_pk_mul_f32 v[98:99], v[8:9], v[102:103]
	v_pk_mul_f32 v[104:105], v[2:3], v[104:105]
	v_pk_mul_f32 v[102:103], v[0:1], v[106:107]
	global_store_dwordx4 v[86:87], v[82:85], off
	global_store_dwordx4 v[86:87], v[94:97], off offset:16
	global_store_dwordx4 v[86:87], v[98:101], off offset:512
	global_store_dwordx4 v[86:87], v[102:105], off offset:528
	s_nop 1
	v_fmamk_f32 v82, v207, 0x3a800000, v203
	v_mul_f32_e32 v83, 0x4b800000, v82
	v_cmp_gt_f32_e32 vcc, s43, v82
	s_nop 1
	v_cndmask_b32_e32 v82, v82, v83, vcc
	v_rsq_f32_e32 v84, v82
	v_lshlrev_b64 v[82:83], 12, v[168:169]
	v_lshl_add_u64 v[82:83], s[72:73], 0, v[82:83]
	v_lshl_add_u64 v[86:87], v[82:83], 0, v[80:81]
	v_mul_f32_e32 v82, 0x45800000, v84
	v_cndmask_b32_e32 v82, v84, v82, vcc
	v_pk_mul_f32 v[94:95], v[150:151], v[82:83] op_sel_hi:[1,0]
;     __device__ __forceinline__ void operator()(Acc& acc, const Unit& u, int wr, int wc, int fr, int fq) const {
;     ...
;         for (int ai = 0; ai < 2; ++ai)
; #pragma unroll
;             for (int m = 0; m < 4; ++m) {
;                 const int row = row0 + ai * HALF + m * 16;
;                 const float r = rsqrtf(__hip_atomic_load(ss + row, __ATOMIC_RELAXED, __HIP_MEMORY_SCOPE_AGENT) * (1.0f / DM) + NORM_EPS);
;                 float* op = out + (size_t)row * DM + col0;
;                 *(f32x4*)op = acc[ai][0][m][0] * r * g00; *(f32x4*)(op + 4) = acc[ai][0][m][1] * r * g01;
;                 *(f32x4*)(op + HALF) = acc[ai][1][m][0] * r * g10; *(f32x4*)(op + HALF + 4) = acc[ai][1][m][1] * r * g11;
; template <class Epi, class Sched, bool ALIGN_EPI>
; __device__ __forceinline__ void gemm_phase(LAS unsigned char* lds, const Gemm g, const Sched& S, const Epi& E) {
;     ...
;         E(acc, cur, wr, wc, fr, fq);
;         if (!has_next) break;
; #pragma unroll
;         for (int a = 0; a < 2; ++a)
; #pragma unroll
;             for (int b = 0; b < 2; ++b)
; #pragma unroll
;                 for (int m = 0; m < 4; ++m)
; #pragma unroll
;                     for (int n = 0; n < 2; ++n) acc[a][b][m][n] = (f32x4){0.f, 0.f, 0.f, 0.f};
;         cur = nxt; cA = nA; cB = nB; ++ui;
	v_pk_mul_f32 v[84:85], v[132:133], v[82:83] op_sel_hi:[1,0]
	v_pk_mul_f32 v[98:99], v[180:181], v[82:83] op_sel_hi:[1,0]
	v_pk_mul_f32 v[96:97], v[134:135], v[82:83] op_sel_hi:[1,0]
	v_pk_mul_f32 v[102:103], v[182:183], v[82:83] op_sel_hi:[1,0]
	v_pk_mul_f32 v[100:101], v[128:129], v[82:83] op_sel_hi:[1,0]
	v_pk_mul_f32 v[106:107], v[184:185], v[82:83] op_sel_hi:[1,0]
	v_pk_mul_f32 v[104:105], v[130:131], v[82:83] op_sel_hi:[1,0]
	v_pk_mul_f32 v[84:85], v[14:15], v[84:85]
	v_pk_mul_f32 v[82:83], v[12:13], v[94:95]
	v_pk_mul_f32 v[96:97], v[6:7], v[96:97]
	v_pk_mul_f32 v[94:95], v[4:5], v[98:99]
	v_pk_mul_f32 v[100:101], v[10:11], v[100:101]
	v_pk_mul_f32 v[98:99], v[8:9], v[102:103]
	v_pk_mul_f32 v[104:105], v[2:3], v[104:105]
	v_pk_mul_f32 v[102:103], v[0:1], v[106:107]
	global_store_dwordx4 v[86:87], v[82:85], off
	global_store_dwordx4 v[86:87], v[94:97], off offset:16
	global_store_dwordx4 v[86:87], v[98:101], off offset:512
	global_store_dwordx4 v[86:87], v[102:105], off offset:528
	s_nop 1
	v_fmamk_f32 v82, v208, 0x3a800000, v203
	v_mul_f32_e32 v83, 0x4b800000, v82
	v_cmp_gt_f32_e32 vcc, s43, v82
	s_nop 1
	v_cndmask_b32_e32 v82, v82, v83, vcc
	v_rsq_f32_e32 v84, v82
	v_lshlrev_b64 v[82:83], 12, v[186:187]
	v_lshl_add_u64 v[82:83], s[72:73], 0, v[82:83]
	v_lshl_add_u64 v[82:83], v[82:83], 0, v[80:81]
	v_mul_f32_e32 v85, 0x45800000, v84
	v_cndmask_b32_e32 v84, v84, v85, vcc
	v_pk_mul_f32 v[60:61], v[60:61], v[84:85] op_sel_hi:[1,0]
	v_pk_mul_f32 v[62:63], v[62:63], v[84:85] op_sel_hi:[1,0]
	v_pk_mul_f32 v[56:57], v[56:57], v[84:85] op_sel_hi:[1,0]
	v_pk_mul_f32 v[58:59], v[58:59], v[84:85] op_sel_hi:[1,0]
	v_pk_mul_f32 v[86:87], v[52:53], v[84:85] op_sel_hi:[1,0]
	v_pk_mul_f32 v[94:95], v[54:55], v[84:85] op_sel_hi:[1,0]
	v_pk_mul_f32 v[96:97], v[48:49], v[84:85] op_sel_hi:[1,0]
	v_pk_mul_f32 v[84:85], v[50:51], v[84:85] op_sel_hi:[1,0]
	v_pk_mul_f32 v[50:51], v[14:15], v[62:63]
	v_pk_mul_f32 v[48:49], v[12:13], v[60:61]
	v_pk_mul_f32 v[54:55], v[6:7], v[58:59]
	v_pk_mul_f32 v[52:53], v[4:5], v[56:57]
	v_pk_mul_f32 v[58:59], v[10:11], v[94:95]
	v_pk_mul_f32 v[56:57], v[8:9], v[86:87]
	v_pk_mul_f32 v[62:63], v[2:3], v[84:85]
	v_pk_mul_f32 v[60:61], v[0:1], v[96:97]
	global_store_dwordx4 v[82:83], v[48:51], off
	global_store_dwordx4 v[82:83], v[52:55], off offset:16
	global_store_dwordx4 v[82:83], v[56:59], off offset:512
	global_store_dwordx4 v[82:83], v[60:63], off offset:528
	s_nop 1
	v_fmamk_f32 v48, v209, 0x3a800000, v203
	v_mul_f32_e32 v49, 0x4b800000, v48
	v_cmp_gt_f32_e32 vcc, s43, v48
	s_nop 1
	v_cndmask_b32_e32 v48, v48, v49, vcc
	v_rsq_f32_e32 v50, v48
	v_lshlrev_b64 v[48:49], 12, v[92:93]
	v_lshl_add_u64 v[48:49], s[72:73], 0, v[48:49]
	v_lshl_add_u64 v[48:49], v[48:49], 0, v[80:81]
	v_mul_f32_e32 v51, 0x45800000, v50
	v_cndmask_b32_e32 v50, v50, v51, vcc
	v_pk_mul_f32 v[44:45], v[44:45], v[50:51] op_sel_hi:[1,0]
	v_pk_mul_f32 v[46:47], v[46:47], v[50:51] op_sel_hi:[1,0]
	v_pk_mul_f32 v[40:41], v[40:41], v[50:51] op_sel_hi:[1,0]
	v_pk_mul_f32 v[42:43], v[42:43], v[50:51] op_sel_hi:[1,0]
	v_pk_mul_f32 v[52:53], v[36:37], v[50:51] op_sel_hi:[1,0]
	v_pk_mul_f32 v[54:55], v[38:39], v[50:51] op_sel_hi:[1,0]
	v_pk_mul_f32 v[56:57], v[32:33], v[50:51] op_sel_hi:[1,0]
	v_pk_mul_f32 v[50:51], v[34:35], v[50:51] op_sel_hi:[1,0]
	v_pk_mul_f32 v[34:35], v[14:15], v[46:47]
	v_pk_mul_f32 v[32:33], v[12:13], v[44:45]
	v_pk_mul_f32 v[38:39], v[6:7], v[42:43]
	v_pk_mul_f32 v[36:37], v[4:5], v[40:41]
	v_pk_mul_f32 v[42:43], v[10:11], v[54:55]
	v_pk_mul_f32 v[40:41], v[8:9], v[52:53]
	v_pk_mul_f32 v[46:47], v[2:3], v[50:51]
	v_pk_mul_f32 v[44:45], v[0:1], v[56:57]
	global_store_dwordx4 v[48:49], v[32:35], off
	global_store_dwordx4 v[48:49], v[36:39], off offset:16
	global_store_dwordx4 v[48:49], v[40:43], off offset:512
	global_store_dwordx4 v[48:49], v[44:47], off offset:528
	s_nop 1
	v_fmamk_f32 v32, v210, 0x3a800000, v203
	v_mul_f32_e32 v33, 0x4b800000, v32
	v_cmp_gt_f32_e32 vcc, s43, v32
	s_nop 1
	v_cndmask_b32_e32 v32, v32, v33, vcc
	v_rsq_f32_e32 v34, v32
	v_lshlrev_b64 v[32:33], 12, v[90:91]
	v_lshl_add_u64 v[32:33], s[72:73], 0, v[32:33]
	v_lshl_add_u64 v[40:41], v[32:33], 0, v[80:81]
	v_mul_f32_e32 v32, 0x45800000, v34
	v_cndmask_b32_e32 v32, v34, v32, vcc
	v_pk_mul_f32 v[28:29], v[28:29], v[32:33] op_sel_hi:[1,0]
	v_pk_mul_f32 v[30:31], v[30:31], v[32:33] op_sel_hi:[1,0]
	v_pk_mul_f32 v[34:35], v[24:25], v[32:33] op_sel_hi:[1,0]
	v_pk_mul_f32 v[36:37], v[26:27], v[32:33] op_sel_hi:[1,0]
	v_pk_mul_f32 v[38:39], v[76:77], v[32:33] op_sel_hi:[1,0]
	v_pk_mul_f32 v[42:43], v[72:73], v[32:33] op_sel_hi:[1,0]
	v_pk_mul_f32 v[44:45], v[78:79], v[32:33] op_sel_hi:[1,0]
	v_pk_mul_f32 v[46:47], v[74:75], v[32:33] op_sel_hi:[1,0]
	v_pk_mul_f32 v[26:27], v[14:15], v[30:31]
	v_pk_mul_f32 v[24:25], v[12:13], v[28:29]
	v_pk_mul_f32 v[30:31], v[6:7], v[36:37]
	v_pk_mul_f32 v[28:29], v[4:5], v[34:35]
	v_pk_mul_f32 v[34:35], v[10:11], v[42:43]
	v_pk_mul_f32 v[32:33], v[8:9], v[38:39]
	v_pk_mul_f32 v[38:39], v[2:3], v[46:47]
	v_pk_mul_f32 v[36:37], v[0:1], v[44:45]
	global_store_dwordx4 v[40:41], v[24:27], off
	global_store_dwordx4 v[40:41], v[28:31], off offset:16
	global_store_dwordx4 v[40:41], v[32:35], off offset:512
	global_store_dwordx4 v[40:41], v[36:39], off offset:528
	v_lshlrev_b64 v[24:25], 12, v[88:89]
	v_lshl_add_u64 v[24:25], s[72:73], 0, v[24:25]
	s_and_b64 vcc, exec, s[4:5]
	v_lshl_add_u64 v[24:25], v[24:25], 0, v[80:81]
	s_mov_b64 s[4:5], -1
	s_nop 1
	v_fmamk_f32 v26, v211, 0x3a800000, v203
	v_mul_f32_e32 v27, 0x4b800000, v26
	v_cmp_gt_f32_e64 s[6:7], s43, v26
	s_nop 1
	v_cndmask_b32_e64 v26, v26, v27, s[6:7]
	v_rsq_f32_e32 v26, v26
	s_nop 0
	v_mul_f32_e32 v27, 0x45800000, v26
	v_cndmask_b32_e64 v26, v26, v27, s[6:7]
	v_pk_mul_f32 v[18:19], v[18:19], v[26:27] op_sel_hi:[1,0]
	v_pk_mul_f32 v[16:17], v[16:17], v[26:27] op_sel_hi:[1,0]
	v_pk_mul_f32 v[22:23], v[22:23], v[26:27] op_sel_hi:[1,0]
	v_pk_mul_f32 v[20:21], v[20:21], v[26:27] op_sel_hi:[1,0]
	v_pk_mul_f32 v[28:29], v[68:69], v[26:27] op_sel_hi:[1,0]
	v_pk_mul_f32 v[30:31], v[64:65], v[26:27] op_sel_hi:[1,0]
	v_pk_mul_f32 v[32:33], v[70:71], v[26:27] op_sel_hi:[1,0]
	v_pk_mul_f32 v[26:27], v[66:67], v[26:27] op_sel_hi:[1,0]
	v_pk_mul_f32 v[14:15], v[14:15], v[16:17]
	v_pk_mul_f32 v[12:13], v[12:13], v[18:19]
	v_pk_mul_f32 v[6:7], v[6:7], v[20:21]
	v_pk_mul_f32 v[4:5], v[4:5], v[22:23]
	v_pk_mul_f32 v[10:11], v[10:11], v[30:31]
	v_pk_mul_f32 v[8:9], v[8:9], v[28:29]
	v_pk_mul_f32 v[2:3], v[2:3], v[26:27]
	v_pk_mul_f32 v[0:1], v[0:1], v[32:33]
	global_store_dwordx4 v[24:25], v[12:15], off
	global_store_dwordx4 v[24:25], v[4:7], off offset:16
	global_store_dwordx4 v[24:25], v[8:11], off offset:512
	global_store_dwordx4 v[24:25], v[0:3], off offset:528
	s_mov_b32 s101, 1
	s_cbranch_vccnz .LBB0_1710
	s_andn2_b64 vcc, exec, s[8:9]
	s_cbranch_vccnz .LBB0_1709
	s_barrier
	s_branch .LBB0_1709
; #define PG8_WAIT_V(n) asm volatile("s_waitcnt vmcnt(" #n ")" ::: "memory")
; #define PG8_BAR __builtin_amdgcn_s_barrier()
; template <class Epi, class Sched, bool ALIGN_EPI>
; __device__ __forceinline__ void gemm_phase(LAS unsigned char* lds, const Gemm g, const Sched& S, const Epi& E) {
;     ...
;     PG8_WAIT_V(0);
;     if constexpr (!ALIGN_EPI) { if (wr == 0) PG8_BAR; }
;     PG8_BAR;
.LBB0_1755:
	s_mov_b32 s101, 0
	s_waitcnt vmcnt(0)
	s_barrier
.LBB0_1756:
	s_cmp_eq_u32 s100, 1
	s_cbranch_scc0 .Lgs_end
	s_mov_b64 exec, 1
	v_mov_b32_e32 v0, 0
	v_mov_b32_e32 v1, 0xffff
	global_atomic_add v0, v1, s[98:99] offset:32
